# adds: MLA step loop barrier-adjacent serial work trimmed (dead pointer-step SALU removed, mask-window bookkeeping moved to softmax start, l accumulation moved before group A's P.V, group B dispatched
# baseline (speedup 1.0000x reference)
.LBB0_146:
	s_mov_b32 s70, s36
	s_cmp_eq_u32 s57, 2
	s_cselect_b64 s[42:43], -1, 0
	s_xor_b64 s[74:75], s[80:81], -1
	s_or_b64 s[42:43], s[74:75], s[42:43]
	s_and_b64 vcc, exec, s[42:43]
	s_cbranch_vccnz .LBB0_148
	v_lshl_add_u32 v210, s37, 14, v218
.Lrot_pvb:
	s_setprio 1
	s_waitcnt lgkmcnt(0)
	s_nop 0
	v_mfma_f32_32x32x16_bf16 v[32:47], v[76:79], v[154:157], v[32:47]
	ds_read_b64_tr_b16 v[80:81], v210 offset:0x200
	ds_read_b64_tr_b16 v[82:83], v210 offset:0xa00
	v_mfma_f32_32x32x16_bf16 v[32:47], v[72:75], v[158:161], v[32:47]
	ds_read_b64_tr_b16 v[84:85], v210 offset:0x1200
	ds_read_b64_tr_b16 v[86:87], v210 offset:0x1a00
	v_mfma_f32_32x32x16_bf16 v[32:47], v[68:71], v[162:165], v[32:47]
	ds_read_b64_tr_b16 v[88:89], v210 offset:0x2200
	ds_read_b64_tr_b16 v[90:91], v210 offset:0x2a00
	v_mfma_f32_32x32x16_bf16 v[32:47], v[64:67], v[206:209], v[32:47]
	ds_read_b64_tr_b16 v[92:93], v210 offset:0x3200
	ds_read_b64_tr_b16 v[94:95], v210 offset:0x3a00
	s_waitcnt lgkmcnt(0)
	v_mfma_f32_32x32x16_bf16 v[48:63], v[76:79], v[80:83], v[48:63]
	ds_read_b64_tr_b16 v[80:81], v210 offset:0x400
	ds_read_b64_tr_b16 v[82:83], v210 offset:0xc00
	v_mfma_f32_32x32x16_bf16 v[48:63], v[72:75], v[84:87], v[48:63]
	ds_read_b64_tr_b16 v[84:85], v210 offset:0x1400
	ds_read_b64_tr_b16 v[86:87], v210 offset:0x1c00
	v_mfma_f32_32x32x16_bf16 v[48:63], v[68:71], v[88:91], v[48:63]
	ds_read_b64_tr_b16 v[88:89], v210 offset:0x2400
	ds_read_b64_tr_b16 v[90:91], v210 offset:0x2c00
	v_mfma_f32_32x32x16_bf16 v[48:63], v[64:67], v[92:95], v[48:63]
	ds_read_b64_tr_b16 v[92:93], v210 offset:0x3400
	ds_read_b64_tr_b16 v[94:95], v210 offset:0x3c00
	s_waitcnt lgkmcnt(0)
	v_mfma_f32_32x32x16_bf16 v[16:31], v[76:79], v[80:83], v[16:31]
	ds_read_b64_tr_b16 v[80:81], v210 offset:0x600
	ds_read_b64_tr_b16 v[82:83], v210 offset:0xe00
	v_mfma_f32_32x32x16_bf16 v[16:31], v[72:75], v[84:87], v[16:31]
	ds_read_b64_tr_b16 v[84:85], v210 offset:0x1600
	ds_read_b64_tr_b16 v[86:87], v210 offset:0x1e00
	v_mfma_f32_32x32x16_bf16 v[16:31], v[68:71], v[88:91], v[16:31]
	ds_read_b64_tr_b16 v[88:89], v210 offset:0x2600
	ds_read_b64_tr_b16 v[90:91], v210 offset:0x2e00
	v_mfma_f32_32x32x16_bf16 v[16:31], v[64:67], v[92:95], v[16:31]
	ds_read_b64_tr_b16 v[92:93], v210 offset:0x3600
	ds_read_b64_tr_b16 v[94:95], v210 offset:0x3e00
	s_waitcnt lgkmcnt(0)
	v_mfma_f32_32x32x16_bf16 v[0:15], v[76:79], v[80:83], v[0:15]
	v_mfma_f32_32x32x16_bf16 v[0:15], v[72:75], v[84:87], v[0:15]
	v_mfma_f32_32x32x16_bf16 v[0:15], v[68:71], v[88:91], v[0:15]
	v_mfma_f32_32x32x16_bf16 v[0:15], v[64:67], v[92:95], v[0:15]
	s_setprio 0

.LBB0_150:
	s_ashr_i32 m0, s100, 7
	s_sub_i32 s69, s69, m0
	s_add_i32 s8, s8, m0
	s_nop 0
	v_max_f32_e32 v210, v81, v81
	v_max_f32_e32 v211, v80, v80
	v_max_f32_e32 v210, v211, v210
	v_max3_f32 v210, v210, v82, v83
	v_max3_f32 v210, v210, v84, v85
	v_max3_f32 v210, v210, v86, v87
	v_max3_f32 v210, v210, v88, v89
	v_max3_f32 v210, v210, v90, v91
	v_max3_f32 v210, v210, v92, v93
	v_max3_f32 v210, v210, v94, v95
	v_max3_f32 v210, v210, v64, v65
	v_max3_f32 v210, v210, v66, v67
	v_max3_f32 v210, v210, v68, v69
	v_max3_f32 v210, v210, v70, v71
	v_max3_f32 v210, v210, v72, v73
	v_max3_f32 v210, v210, v74, v75
	v_max3_f32 v210, v210, v76, v77
	v_max3_f32 v210, v210, v78, v79
	v_mov_b32_e32 v211, v210
	s_nop 1
	v_permlane32_swap_b32_e32 v210, v211
	v_max_f32_e32 v211, v211, v211
	v_max_f32_e32 v210, v210, v210
	v_max_f32_e32 v210, v210, v211
	v_sub_f32_e32 v211, v210, v232
	v_cmp_ge_f32_e32 vcc, s68, v211
	v_max_f32_e32 v211, v232, v232
	v_max_f32_e32 v235, v211, v210
	v_sub_f32_e32 v210, v232, v235
	v_mul_f32_e32 v210, 0x3fb8aa3b, v210
	v_exp_f32_e32 v210, v210
	s_cmp_eq_u64 vcc, exec
	s_cselect_b64 s[42:43], -1, 0
	v_cndmask_b32_e64 v234, v210, 1.0, s[42:43]
	v_cmp_gt_f32_e32 vcc, 1.0, v234
	s_cbranch_vccz .LBB0_154
	s_and_saveexec_b64 s[36:37], s[38:39]
	ds_write_b32 v205, v234 offset:128
	s_or_b64 exec, exec, s[36:37]
	s_waitcnt lgkmcnt(0)
	ds_read_b128 v[240:243], v203 offset:224
	ds_read_b128 v[244:247], v203 offset:192
	ds_read_b128 v[248:251], v203 offset:160
	ds_read_b128 v[210:213], v203 offset:128
	s_waitcnt lgkmcnt(3)
	v_pk_mul_f32 v[46:47], v[46:47], v[242:243]
	s_waitcnt lgkmcnt(2)
	v_pk_mul_f32 v[42:43], v[42:43], v[246:247]
	s_waitcnt lgkmcnt(1)
	v_pk_mul_f32 v[38:39], v[38:39], v[250:251]
	s_waitcnt lgkmcnt(0)
	v_pk_mul_f32 v[34:35], v[34:35], v[212:213]
	v_pk_mul_f32 v[44:45], v[44:45], v[240:241]
	v_pk_mul_f32 v[40:41], v[40:41], v[244:245]
	v_pk_mul_f32 v[36:37], v[36:37], v[248:249]
	v_pk_mul_f32 v[32:33], v[32:33], v[210:211]
	v_pk_mul_f32 v[62:63], v[62:63], v[242:243]
	v_pk_mul_f32 v[58:59], v[58:59], v[246:247]
	v_pk_mul_f32 v[54:55], v[54:55], v[250:251]
	v_pk_mul_f32 v[50:51], v[50:51], v[212:213]
	v_pk_mul_f32 v[60:61], v[60:61], v[240:241]
	v_pk_mul_f32 v[56:57], v[56:57], v[244:245]
	v_pk_mul_f32 v[52:53], v[52:53], v[248:249]
	v_pk_mul_f32 v[48:49], v[48:49], v[210:211]
	v_pk_mul_f32 v[30:31], v[30:31], v[242:243]
	v_pk_mul_f32 v[26:27], v[26:27], v[246:247]
	v_pk_mul_f32 v[22:23], v[22:23], v[250:251]
	v_pk_mul_f32 v[18:19], v[18:19], v[212:213]
	v_pk_mul_f32 v[28:29], v[28:29], v[240:241]
	v_pk_mul_f32 v[24:25], v[24:25], v[244:245]
	v_pk_mul_f32 v[20:21], v[20:21], v[248:249]
	v_pk_mul_f32 v[16:17], v[16:17], v[210:211]
	v_pk_mul_f32 v[14:15], v[14:15], v[242:243]
	v_pk_mul_f32 v[10:11], v[10:11], v[246:247]
	v_pk_mul_f32 v[6:7], v[6:7], v[250:251]
	v_pk_mul_f32 v[2:3], v[2:3], v[212:213]
	v_pk_mul_f32 v[12:13], v[12:13], v[240:241]
	v_pk_mul_f32 v[8:9], v[8:9], v[244:245]
	v_pk_mul_f32 v[4:5], v[4:5], v[248:249]
	v_pk_mul_f32 v[0:1], v[0:1], v[210:211]
.LBB0_154:
	v_cndmask_b32_e64 v232, v235, v232, s[42:43]
	v_mul_f32_e32 v210, 0xbfb8aa3b, v232
	v_fmamk_f32 v80, v80, 0x3fb8aa3b, v210
	v_fmamk_f32 v81, v81, 0x3fb8aa3b, v210
	v_fmamk_f32 v82, v82, 0x3fb8aa3b, v210
	v_fmamk_f32 v83, v83, 0x3fb8aa3b, v210
	v_fmamk_f32 v84, v84, 0x3fb8aa3b, v210
	v_fmamk_f32 v85, v85, 0x3fb8aa3b, v210
	v_fmamk_f32 v86, v86, 0x3fb8aa3b, v210
	v_fmamk_f32 v87, v87, 0x3fb8aa3b, v210
	v_fmamk_f32 v88, v88, 0x3fb8aa3b, v210
	v_fmamk_f32 v89, v89, 0x3fb8aa3b, v210
	v_fmamk_f32 v90, v90, 0x3fb8aa3b, v210
	v_fmamk_f32 v91, v91, 0x3fb8aa3b, v210
	v_fmamk_f32 v92, v92, 0x3fb8aa3b, v210
	v_fmamk_f32 v93, v93, 0x3fb8aa3b, v210
	v_fmamk_f32 v94, v94, 0x3fb8aa3b, v210
	v_fmamk_f32 v95, v95, 0x3fb8aa3b, v210
	v_fmamk_f32 v64, v64, 0x3fb8aa3b, v210
	v_fmamk_f32 v65, v65, 0x3fb8aa3b, v210
	v_fmamk_f32 v66, v66, 0x3fb8aa3b, v210
	v_fmamk_f32 v67, v67, 0x3fb8aa3b, v210
	v_fmamk_f32 v68, v68, 0x3fb8aa3b, v210
	v_fmamk_f32 v69, v69, 0x3fb8aa3b, v210
	v_fmamk_f32 v70, v70, 0x3fb8aa3b, v210
	v_fmamk_f32 v71, v71, 0x3fb8aa3b, v210
	v_fmamk_f32 v72, v72, 0x3fb8aa3b, v210
	v_fmamk_f32 v73, v73, 0x3fb8aa3b, v210
	v_fmamk_f32 v74, v74, 0x3fb8aa3b, v210
	v_fmamk_f32 v75, v75, 0x3fb8aa3b, v210
	v_fmamk_f32 v76, v76, 0x3fb8aa3b, v210
	v_fmamk_f32 v77, v77, 0x3fb8aa3b, v210
	v_fmamk_f32 v78, v78, 0x3fb8aa3b, v210
	v_fmac_f32_e32 v210, 0x3fb8aa3b, v79
	v_exp_f32_e32 v79, v80
	v_exp_f32_e32 v211, v81
	v_exp_f32_e32 v82, v82
	v_exp_f32_e32 v83, v83
	v_exp_f32_e32 v84, v84
	v_exp_f32_e32 v212, v68
	v_add_f32_e32 v68, 0, v79
	v_exp_f32_e32 v85, v85
	v_add_f32_e32 v68, v211, v68
	v_exp_f32_e32 v86, v86
	v_add_f32_e32 v68, v82, v68
	v_exp_f32_e32 v87, v87
	v_add_f32_e32 v68, v83, v68
	v_exp_f32_e32 v88, v88
	v_add_f32_e32 v68, v84, v68
	v_exp_f32_e32 v89, v89
	v_add_f32_e32 v68, v85, v68
	v_exp_f32_e32 v90, v90
	v_add_f32_e32 v68, v86, v68
	v_exp_f32_e32 v91, v91
	v_add_f32_e32 v68, v87, v68
	v_exp_f32_e32 v92, v92
	v_add_f32_e32 v68, v88, v68
	v_exp_f32_e32 v93, v93
	v_add_f32_e32 v68, v89, v68
	v_exp_f32_e32 v94, v94
	v_add_f32_e32 v68, v90, v68
	v_exp_f32_e32 v95, v95
	v_add_f32_e32 v68, v91, v68
	v_exp_f32_e32 v64, v64
	v_add_f32_e32 v68, v92, v68
	v_exp_f32_e32 v65, v65
	v_add_f32_e32 v68, v93, v68
	v_exp_f32_e32 v66, v66
	v_add_f32_e32 v68, v94, v68
	v_exp_f32_e32 v67, v67
	v_add_f32_e32 v68, v95, v68
	v_add_f32_e32 v68, v64, v68
	v_exp_f32_e32 v213, v69
	v_add_f32_e32 v68, v65, v68
	v_exp_f32_e32 v235, v70
	v_add_f32_e32 v68, v66, v68
	v_exp_f32_e32 v71, v71
	v_add_f32_e32 v68, v67, v68
	v_exp_f32_e32 v240, v72
	v_add_f32_e32 v68, v212, v68
	v_exp_f32_e32 v241, v73
	v_add_f32_e32 v68, v213, v68
	v_exp_f32_e32 v242, v74
	v_add_f32_e32 v68, v235, v68
	v_exp_f32_e32 v243, v75
	v_add_f32_e32 v68, v71, v68
	v_exp_f32_e32 v244, v76
	v_add_f32_e32 v68, v240, v68
	v_exp_f32_e32 v245, v77
	v_add_f32_e32 v68, v241, v68
	v_exp_f32_e32 v246, v78
	v_add_f32_e32 v68, v242, v68
	v_exp_f32_e32 v210, v210
	v_add_f32_e32 v68, v243, v68
	v_add_f32_e32 v68, v244, v68
	v_add_f32_e32 v68, v245, v68
	v_add_f32_e32 v68, v246, v68
	v_add_f32_e32 v80, v210, v68
	v_mov_b32_e32 v81, v80
	v_cvt_pk_bf16_f32 v76, v79, v211
	v_cvt_pk_bf16_f32 v77, v82, v83
	v_cvt_pk_bf16_f32 v78, v84, v85
	v_cvt_pk_bf16_f32 v79, v86, v87
	v_cvt_pk_bf16_f32 v72, v88, v89
	v_cvt_pk_bf16_f32 v73, v90, v91
	v_cvt_pk_bf16_f32 v74, v92, v93
	v_cvt_pk_bf16_f32 v75, v94, v95
	v_cvt_pk_bf16_f32 v68, v64, v65
	v_cvt_pk_bf16_f32 v69, v66, v67
	v_cvt_pk_bf16_f32 v70, v212, v213
	v_cvt_pk_bf16_f32 v71, v235, v71
	v_cvt_pk_bf16_f32 v64, v240, v241
	v_cvt_pk_bf16_f32 v65, v242, v243
	v_cvt_pk_bf16_f32 v66, v244, v245
	v_cvt_pk_bf16_f32 v67, v246, v210
	s_nop 1
	v_permlane32_swap_b32_e32 v80, v81
	v_permlane32_swap_b32_e32 v76, v78
	v_permlane32_swap_b32_e32 v77, v79
	v_permlane32_swap_b32_e32 v72, v74
	v_permlane32_swap_b32_e32 v73, v75
	v_permlane32_swap_b32_e32 v68, v70
	v_permlane32_swap_b32_e32 v69, v71
	v_permlane32_swap_b32_e32 v64, v66
	v_permlane32_swap_b32_e32 v65, v67
	v_add_f32_e32 v80, v80, v81
	v_fmac_f32_e32 v80, v233, v234
	s_andn2_b64 vcc, exec, s[76:77]
	s_cbranch_vccnz .LBB0_156
	v_lshl_add_u32 v94, s70, 14, v218
	ds_read_b64_tr_b16 v[82:83], v94 offset:0
	ds_read_b64_tr_b16 v[84:85], v94 offset:0x800
	ds_read_b64_tr_b16 v[86:87], v94 offset:0x1000
	ds_read_b64_tr_b16 v[88:89], v94 offset:0x1800
	ds_read_b64_tr_b16 v[90:91], v94 offset:0x2000
	ds_read_b64_tr_b16 v[92:93], v94 offset:0x2800
	ds_read_b64_tr_b16 v[210:211], v94 offset:0x3000
	ds_read_b64_tr_b16 v[212:213], v94 offset:0x3800
	s_waitcnt lgkmcnt(0)
	s_nop 0
	v_mfma_f32_32x32x16_bf16 v[32:47], v[76:79], v[82:85], v[32:47]
	ds_read_b64_tr_b16 v[82:83], v94 offset:0x200
	ds_read_b64_tr_b16 v[84:85], v94 offset:0xa00
	v_mfma_f32_32x32x16_bf16 v[32:47], v[72:75], v[86:89], v[32:47]
	ds_read_b64_tr_b16 v[86:87], v94 offset:0x1200
	ds_read_b64_tr_b16 v[88:89], v94 offset:0x1a00
	v_mfma_f32_32x32x16_bf16 v[32:47], v[68:71], v[90:93], v[32:47]
	ds_read_b64_tr_b16 v[90:91], v94 offset:0x2200
	ds_read_b64_tr_b16 v[92:93], v94 offset:0x2a00
	v_mfma_f32_32x32x16_bf16 v[32:47], v[64:67], v[210:213], v[32:47]
	ds_read_b64_tr_b16 v[210:211], v94 offset:0x3200
	ds_read_b64_tr_b16 v[212:213], v94 offset:0x3a00
	s_waitcnt lgkmcnt(0)
	v_mfma_f32_32x32x16_bf16 v[48:63], v[76:79], v[82:85], v[48:63]
	ds_read_b64_tr_b16 v[82:83], v94 offset:0x400
	ds_read_b64_tr_b16 v[84:85], v94 offset:0xc00
	v_mfma_f32_32x32x16_bf16 v[48:63], v[72:75], v[86:89], v[48:63]
	ds_read_b64_tr_b16 v[86:87], v94 offset:0x1400
	ds_read_b64_tr_b16 v[88:89], v94 offset:0x1c00
	v_mfma_f32_32x32x16_bf16 v[48:63], v[68:71], v[90:93], v[48:63]
	ds_read_b64_tr_b16 v[90:91], v94 offset:0x2400
	ds_read_b64_tr_b16 v[92:93], v94 offset:0x2c00
	v_mfma_f32_32x32x16_bf16 v[48:63], v[64:67], v[210:213], v[48:63]
	ds_read_b64_tr_b16 v[210:211], v94 offset:0x3400
	ds_read_b64_tr_b16 v[212:213], v94 offset:0x3c00
	s_waitcnt lgkmcnt(0)
	v_mfma_f32_32x32x16_bf16 v[16:31], v[76:79], v[82:85], v[16:31]
	ds_read_b64_tr_b16 v[82:83], v94 offset:0x600
	ds_read_b64_tr_b16 v[84:85], v94 offset:0xe00
	v_mfma_f32_32x32x16_bf16 v[16:31], v[72:75], v[86:89], v[16:31]
	ds_read_b64_tr_b16 v[86:87], v94 offset:0x1600
	ds_read_b64_tr_b16 v[88:89], v94 offset:0x1e00
	v_mfma_f32_32x32x16_bf16 v[16:31], v[68:71], v[90:93], v[16:31]
	ds_read_b64_tr_b16 v[90:91], v94 offset:0x2600
	ds_read_b64_tr_b16 v[92:93], v94 offset:0x2e00
	v_mfma_f32_32x32x16_bf16 v[16:31], v[64:67], v[210:213], v[16:31]
	ds_read_b64_tr_b16 v[210:211], v94 offset:0x3600
	ds_read_b64_tr_b16 v[212:213], v94 offset:0x3e00
	s_waitcnt lgkmcnt(0)
	v_mfma_f32_32x32x16_bf16 v[0:15], v[76:79], v[82:85], v[0:15]
	v_mfma_f32_32x32x16_bf16 v[0:15], v[72:75], v[86:89], v[0:15]
	v_mfma_f32_32x32x16_bf16 v[0:15], v[68:71], v[90:93], v[0:15]
	v_mfma_f32_32x32x16_bf16 v[0:15], v[64:67], v[210:213], v[0:15]

.Lpv3_bskip:
.LBB0_159:
	s_add_i32 s57, s57, 1
	s_add_i32 s37, s63, s57
	s_and_b64 vcc, exec, s[80:81]
	s_cmp_eq_u32 s37, 2
	s_mov_b32 s37, s70
	v_mov_b32_e32 v233, v80
	s_barrier
	s_cbranch_scc1 .LBB0_161
	s_mov_b32 s70, s36
	s_cbranch_vccnz .Lrot_pvb
	s_branch .LBB0_148
